# static s_setprio 1 for waves 0-3 also in the two GLA item phases (on top of the attention prompt-unit raise)
# speedup vs baseline: 1.0065x; 1.0065x over previous
; #define REP(k) _Pragma("unroll 1") for (int rep_ = 0; rep_ < ((((DUP_MASK) >> (k)) & 1) ? 2 : 1); ++rep_)
; __device__ __forceinline__ void gla_prefetch(GlaPre& pf, const Args& a, int cid, int h) {
;     const int tid = threadIdx.x, dvv = tid & 255, th = tid >> 8, row0 = cid * 64;
;     const bf16_t* vp = (const bf16_t*)(a.ws + WS_PROJ) + (size_t)(row0 + 32 * th) * NPJ + 1024 + h * 256 + dvv;
; #pragma unroll
;     for (int i = 0; i < 32; ++i) pf.v[i] = vp[(size_t)i * NPJ];
;     pf.gl = *(const f32x4*)((const float*)(a.ws + WS_GL) + (size_t)(row0 + ((tid & 255) >> 2)) * 16 + (tid & 3) * 4);
; __global__ void __launch_bounds__(512, 2) fwd(Args a) {
;     ...
;     if (IN(2)) REP(2) {
;         if (G == 256 && !MK_MULTI) {
;             GlaPre pf; gla_prefetch(pf, a, vcu >> 2, vcu & 3);
;             const int it4 = 1024 + (vcu & 127);
; #pragma unroll 1
;             for (int it = vcu; it < 1024; it += G) gla_item<0>(a, lds, it >> 2, it & 3, pf, (it + G < 1024) ? it + G : it4);
;             if (vcu < 128) gla_item<0>(a, lds, it4 >> 2, it4 & 3, pf, -1);
;             else gla_item<1>(a, lds, it4 >> 2, it4 & 3, pf, -1);
;         } else {
;             GlaPre pf; if (vcu < 1152) gla_prefetch(pf, a, vcu >> 2, vcu & 3);
; #pragma unroll 1
;             for (int it = vcu; it < 1152; it += G) gla_item<0>(a, lds, it >> 2, it & 3, pf, (it + G < 1152) ? it + G : -1);
.LBB0_371:
	s_cmp_lt_i32 s30, 3
	s_cselect_b64 s[10:11], -1, 0
	s_and_b64 s[0:1], s[10:11], s[0:1]
	s_andn2_b64 vcc, exec, s[0:1]
	v_lshrrev_b32_e32 v168, 3, v0
	v_lshlrev_b32_e32 v169, 4, v0
	s_cbranch_vccnz .LBB0_488
	v_readfirstlane_b32 s98, v0
	s_nop 3
	s_lshr_b32 s98, s98, 6
	s_cmp_ge_u32 s98, 4
	s_cbranch_scc1 .Lprio_done_p2
	s_setprio 1
.Lprio_done_p2:
	s_lshl_b32 s3, s96, 4
	s_and_b32 s6, s3, 0xffffffc0
	v_and_b32_e32 v121, 32, v168
	v_or_b32_e32 v4, s6, v121
	s_movk_i32 s4, 0x1800
	v_mov_b64_e32 v[2:3], s[28:29]
	v_bfe_u32 v122, v0, 2, 6
	s_add_u32 s0, s28, 0x10e00000
	v_readlane_b32 s52, v252, 0
	v_mad_i64_i32 v[2:3], s[4:5], v4, s4, v[2:3]
	v_or_b32_e32 v4, s6, v122
	s_addc_u32 s1, s29, 0
	v_readlane_b32 s58, v252, 6
	v_ashrrev_i32_e32 v5, 31, v4
	v_readlane_b32 s59, v252, 7
	s_add_u32 s42, s58, 0xcd00000
	s_mov_b64 s[4:5], 0xa200800
	v_lshlrev_b64 v[4:5], 6, v[4:5]
	s_addc_u32 s43, s59, 0
	v_lshl_add_u64 v[114:115], v[2:3], 0, s[4:5]
	v_mov_b32_e32 v3, 0
	v_lshl_add_u64 v[4:5], s[0:1], 0, v[4:5]
	v_and_b32_e32 v2, 48, v169
	s_cmpk_lg_i32 s34, 0x100
	v_lshl_add_u64 v[112:113], v[4:5], 0, v[2:3]
	v_lshl_add_u64 v[110:111], s[0:1], 0, v[2:3]
	s_mov_b64 s[0:1], -1
	v_readlane_b32 s53, v252, 1
	v_readlane_b32 s54, v252, 2
	v_readlane_b32 s55, v252, 3
	v_readlane_b32 s56, v252, 4
	v_readlane_b32 s57, v252, 5
	s_cbranch_scc0 .LBB0_454
	s_cmpk_lt_i32 s96, 0x480
	s_cselect_b64 s[0:1], -1, 0
	s_cmpk_gt_i32 s96, 0x47f
	s_cbranch_scc1 .LBB0_375
	s_lshl_b32 s4, s96, 9
	s_and_b32 s4, s4, 0x600
	s_mov_b32 s5, 0
	v_mov_b32_e32 v4, 1
	v_lshl_add_u64 v[2:3], v[114:115], 0, s[4:5]
	v_lshlrev_b32_sdwa v4, v4, v0 dst_sel:DWORD dst_unused:UNUSED_PAD src0_sel:DWORD src1_sel:BYTE_0
	v_mov_b32_e32 v5, 0
	v_lshl_add_u64 v[2:3], v[2:3], 0, v[4:5]
	v_add_co_u32_e32 v4, vcc, 0x1000, v2
	s_nop 1
	v_addc_co_u32_e32 v5, vcc, 0, v3, vcc
	v_add_co_u32_e32 v6, vcc, 0x3000, v2
	s_nop 1
	v_addc_co_u32_e32 v7, vcc, 0, v3, vcc
	v_add_co_u32_e32 v8, vcc, 0x4000, v2
	s_nop 1
	v_addc_co_u32_e32 v9, vcc, 0, v3, vcc
	v_add_co_u32_e32 v10, vcc, 0x6000, v2
	s_nop 1
	v_addc_co_u32_e32 v11, vcc, 0, v3, vcc
	v_add_co_u32_e32 v12, vcc, 0x7000, v2
	s_nop 1
	v_addc_co_u32_e32 v13, vcc, 0, v3, vcc
	v_add_co_u32_e32 v14, vcc, 0x9000, v2
	s_nop 1
	v_addc_co_u32_e32 v15, vcc, 0, v3, vcc
	v_add_co_u32_e32 v16, vcc, 0xa000, v2
	s_nop 1
	v_addc_co_u32_e32 v17, vcc, 0, v3, vcc
	v_add_co_u32_e32 v18, vcc, 0xc000, v2
	s_nop 1
	v_addc_co_u32_e32 v19, vcc, 0, v3, vcc
	v_add_co_u32_e32 v20, vcc, 0xd000, v2
	s_nop 1
	v_addc_co_u32_e32 v21, vcc, 0, v3, vcc
	v_add_co_u32_e32 v22, vcc, 0xf000, v2
	s_nop 1
	v_addc_co_u32_e32 v23, vcc, 0, v3, vcc
	global_load_ushort v119, v[8:9], off offset:2048
	global_load_ushort v123, v[10:11], off
	global_load_ushort v124, v[12:13], off offset:2048
	global_load_ushort v125, v[14:15], off
	global_load_ushort v126, v[16:17], off offset:2048
	global_load_ushort v127, v[18:19], off
	global_load_ushort v128, v[20:21], off offset:2048
	global_load_ushort v129, v[22:23], off
	v_add_co_u32_e32 v8, vcc, 0x10000, v2
	s_nop 1
	v_addc_co_u32_e32 v9, vcc, 0, v3, vcc
	v_add_co_u32_e32 v10, vcc, 0x12000, v2
	s_nop 1
	v_addc_co_u32_e32 v11, vcc, 0, v3, vcc
	v_add_co_u32_e32 v12, vcc, 0x13000, v2
	s_nop 1
	v_addc_co_u32_e32 v13, vcc, 0, v3, vcc
	v_add_co_u32_e32 v14, vcc, 0x15000, v2
	s_nop 1
	v_addc_co_u32_e32 v15, vcc, 0, v3, vcc
	v_add_co_u32_e32 v16, vcc, 0x16000, v2
	s_nop 1
	v_addc_co_u32_e32 v17, vcc, 0, v3, vcc
	v_add_co_u32_e32 v18, vcc, 0x18000, v2
	s_nop 1
	v_addc_co_u32_e32 v19, vcc, 0, v3, vcc
	v_add_co_u32_e32 v20, vcc, 0x19000, v2
	s_nop 1
	v_addc_co_u32_e32 v21, vcc, 0, v3, vcc
	v_add_co_u32_e32 v22, vcc, 0x1b000, v2
	s_nop 1
	v_addc_co_u32_e32 v23, vcc, 0, v3, vcc
	global_load_ushort v132, v[8:9], off offset:2048
	global_load_ushort v134, v[10:11], off
	global_load_ushort v135, v[12:13], off offset:2048
	global_load_ushort v136, v[14:15], off
	global_load_ushort v137, v[16:17], off offset:2048
	global_load_ushort v138, v[18:19], off
	global_load_ushort v139, v[20:21], off offset:2048
	global_load_ushort v140, v[22:23], off
	v_add_co_u32_e32 v8, vcc, 0x1c000, v2
	s_nop 1
	v_addc_co_u32_e32 v9, vcc, 0, v3, vcc
	v_add_co_u32_e32 v10, vcc, 0x1e000, v2
	s_nop 1
	v_addc_co_u32_e32 v11, vcc, 0, v3, vcc
	v_add_co_u32_e32 v12, vcc, 0x1f000, v2
	s_nop 1
	v_addc_co_u32_e32 v13, vcc, 0, v3, vcc
	v_add_co_u32_e32 v14, vcc, 0x21000, v2
	s_nop 1
	v_addc_co_u32_e32 v15, vcc, 0, v3, vcc
	v_add_co_u32_e32 v16, vcc, 0x22000, v2
	s_nop 1
	v_addc_co_u32_e32 v17, vcc, 0, v3, vcc
	v_add_co_u32_e32 v18, vcc, 0x24000, v2
	s_nop 1
	v_addc_co_u32_e32 v19, vcc, 0, v3, vcc
	v_add_co_u32_e32 v20, vcc, 0x25000, v2
	s_nop 1
	v_addc_co_u32_e32 v21, vcc, 0, v3, vcc
	v_add_co_u32_e32 v22, vcc, 0x27000, v2
	s_nop 1
	v_addc_co_u32_e32 v23, vcc, 0, v3, vcc
	global_load_ushort v142, v[8:9], off offset:2048
	global_load_ushort v143, v[10:11], off
	global_load_ushort v144, v[12:13], off offset:2048
	global_load_ushort v145, v[14:15], off
	global_load_ushort v146, v[16:17], off offset:2048
	global_load_ushort v147, v[18:19], off
	global_load_ushort v148, v[20:21], off offset:2048
	global_load_ushort v149, v[22:23], off
	v_add_co_u32_e32 v8, vcc, 0x28000, v2
	s_nop 1
	v_addc_co_u32_e32 v9, vcc, 0, v3, vcc
	v_add_co_u32_e32 v10, vcc, 0x2a000, v2
	s_nop 1
	v_addc_co_u32_e32 v11, vcc, 0, v3, vcc
	v_add_co_u32_e32 v12, vcc, 0x2b000, v2
	s_nop 1
	v_addc_co_u32_e32 v13, vcc, 0, v3, vcc
	v_add_co_u32_e32 v14, vcc, 0x2d000, v2
	s_nop 1
	v_addc_co_u32_e32 v15, vcc, 0, v3, vcc
	v_add_co_u32_e32 v16, vcc, 0x2e000, v2
	s_nop 1
	v_addc_co_u32_e32 v17, vcc, 0, v3, vcc
	global_load_ushort v150, v[8:9], off offset:2048
	global_load_ushort v151, v[10:11], off
	global_load_ushort v152, v[12:13], off offset:2048
	global_load_ushort v153, v[14:15], off
	global_load_ushort v154, v[16:17], off offset:2048
	global_load_ushort v130, v[2:3], off
	global_load_ushort v131, v[4:5], off offset:2048
	global_load_ushort v133, v[6:7], off
	global_load_dwordx4 v[98:101], v[112:113], off
	s_andn2_b64 vcc, exec, s[0:1]
	s_cbranch_vccz .LBB0_376
	s_branch .LBB0_453

; #define SEAM(k) do { if (IN(k) && IN((k) + 1)) { if ((k) == 0 && a.ph_hi < 0) cg::this_grid().sync(); xcd_barrier(xbar); } } while (0)
; __device__ __forceinline__ void xcd_barrier(const XcdBarrier& b) {
;     asm volatile("s_waitcnt vmcnt(0)" ::: "memory");
;     __syncthreads();
;     if (threadIdx.x == 0) {
;         unsigned* bar = b.bar;
;         __builtin_amdgcn_s_waitcnt(0);
;         unsigned nloc = b.st[0], nx = b.st[1];
;         if (nloc == 0u) { xcd_barrier_complete(bar, b.x, nloc, nx); b.st[0] = nloc; b.st[1] = nx; }
; __global__ void __launch_bounds__(512, 2) fwd(Args a) {
;     ...
;     SEAM(2);
.LBB0_488:
	s_setprio 0
	s_cmp_gt_i32 s31, 3
	s_cselect_b64 s[0:1], -1, 0
	s_and_b64 s[4:5], s[10:11], s[0:1]
	s_andn2_b64 vcc, exec, s[4:5]
	s_cbranch_vccnz .LBB0_538
	s_waitcnt vmcnt(0)
	v_cmp_eq_u32_e32 vcc, 0, v0
	s_waitcnt lgkmcnt(0)
	s_barrier
	s_and_saveexec_b64 s[4:5], vcc
	s_cbranch_execz .LBB0_537
	v_mov_b32_e32 v2, s97
	s_waitcnt vmcnt(0) expcnt(0) lgkmcnt(0)
	ds_read_b32 v4, v2
	ds_read_b32 v2, v2 offset:4
	s_waitcnt lgkmcnt(1)
	v_cmp_ne_u32_e32 vcc, 0, v4
	s_cbranch_vccnz .LBB0_505
	v_readlane_b32 s6, v252, 8
	v_readlane_b32 s7, v252, 9
	s_load_dwordx2 s[10:11], s[6:7], 0x4
	s_add_u32 s6, s28, 0x1000
	s_addc_u32 s7, s29, 0
	s_add_u32 s8, s28, 0x1100
	s_addc_u32 s9, s29, 0
	s_waitcnt lgkmcnt(0)
	s_mul_i32 s3, s10, s34
	s_add_u32 s10, s28, 0x1200
	s_mul_i32 s3, s3, s11
	s_addc_u32 s11, s29, 0
	s_add_u32 s42, s28, 0x1300
	s_addc_u32 s43, s29, 0
	s_mov_b32 s35, 1
	v_mov_b32_e32 v18, 0
	s_branch .LBB0_493

; #define REP(k) _Pragma("unroll 1") for (int rep_ = 0; rep_ < ((((DUP_MASK) >> (k)) & 1) ? 2 : 1); ++rep_)
; __device__ __forceinline__ void gla_prefetch(GlaPre& pf, const Args& a, int cid, int h) {
;     const int tid = threadIdx.x, dvv = tid & 255, th = tid >> 8, row0 = cid * 64;
;     const bf16_t* vp = (const bf16_t*)(a.ws + WS_PROJ) + (size_t)(row0 + 32 * th) * NPJ + 1024 + h * 256 + dvv;
; #pragma unroll
;     for (int i = 0; i < 32; ++i) pf.v[i] = vp[(size_t)i * NPJ];
;     pf.gl = *(const f32x4*)((const float*)(a.ws + WS_GL) + (size_t)(row0 + ((tid & 255) >> 2)) * 16 + (tid & 3) * 4);
; __global__ void __launch_bounds__(512, 2) fwd(Args a) {
;     ...
;     if (IN(4)) REP(4) {
;         { const int nit = (G == 256 && !MK_MULTI) ? 1024 : 1152;
;         GlaPre pf; if (vcu < nit) gla_prefetch(pf, a, vcu >> 2, vcu & 3);
; #pragma unroll 1
;         for (int it = vcu; it < nit; it += G) gla_item<1>(a, lds, it >> 2, it & 3, pf, (it + G < nit) ? it + G : -1); }
.LBB0_696:
	s_cmp_lt_i32 s30, 5
	s_cselect_b64 s[4:5], -1, 0
	s_and_b64 s[0:1], s[4:5], s[0:1]
	s_andn2_b64 vcc, exec, s[0:1]
	s_cbranch_vccnz .LBB0_721
	v_readfirstlane_b32 s98, v0
	s_nop 3
	s_lshr_b32 s98, s98, 6
	s_cmp_ge_u32 s98, 4
	s_cbranch_scc1 .Lprio_done_p4
	s_setprio 1
.Lprio_done_p4:
	s_cmpk_eq_i32 s34, 0x100
	s_movk_i32 s0, 0x400
	s_cselect_b32 s3, s0, 0x480
	s_cmp_ge_i32 s96, s3
	s_cbranch_scc1 .LBB0_721
	s_add_u32 s6, s28, 0x19100000
	s_addc_u32 s7, s29, 0
	s_add_u32 s0, s28, 0x10e00000
	s_addc_u32 s1, s29, 0
	s_add_u32 s60, s28, 0x1d100000
	s_addc_u32 s61, s29, 0
	s_lshl_b32 s8, s96, 4
	s_waitcnt vmcnt(2)
	v_bfe_u32 v87, v0, 2, 6
	s_andn2_b32 s8, s8, 63
	v_or_b32_e32 v4, s8, v87
	v_and_b32_e32 v86, 32, v168
	v_ashrrev_i32_e32 v5, 31, v4
	s_waitcnt vmcnt(0)
	v_mov_b32_e32 v67, 0
	v_and_b32_e32 v66, 48, v169
	v_lshlrev_b64 v[4:5], 6, v[4:5]
	s_waitcnt lgkmcnt(0)
	v_or_b32_e32 v3, s8, v86
	s_movk_i32 s62, 0x1800
	v_mov_b64_e32 v[6:7], s[28:29]
	v_lshl_add_u64 v[68:69], s[0:1], 0, v[66:67]
	v_lshl_add_u64 v[4:5], s[0:1], 0, v[4:5]
	v_mad_i64_i32 v[6:7], s[0:1], v3, s62, v[6:7]
	s_lshl_b32 s0, s96, 9
	v_and_b32_e32 v2, 0xff, v0
	s_mov_b32 s9, 0
	s_and_b32 s8, s0, 0x600
	v_lshl_add_u64 v[4:5], v[4:5], 0, v[66:67]
	v_lshl_add_u64 v[6:7], v[6:7], 0, s[8:9]
	v_lshlrev_b32_e32 v66, 1, v2
	v_lshl_add_u64 v[6:7], v[6:7], 0, v[66:67]
	s_mov_b32 s0, 0xa200000
	v_add_co_u32_e32 v8, vcc, s0, v6
	s_mov_b32 s0, 0xa202000
	s_nop 0
	v_addc_co_u32_e32 v9, vcc, 0, v7, vcc
	v_add_co_u32_e32 v10, vcc, s0, v6
	s_mov_b32 s0, 0xa203000
	s_nop 0
	v_addc_co_u32_e32 v11, vcc, 0, v7, vcc
	v_add_co_u32_e32 v12, vcc, s0, v6
	s_mov_b32 s0, 0xa205000
	s_nop 0
	v_addc_co_u32_e32 v13, vcc, 0, v7, vcc
	v_add_co_u32_e32 v14, vcc, s0, v6
	s_mov_b32 s0, 0xa206000
	s_nop 0
	v_addc_co_u32_e32 v15, vcc, 0, v7, vcc
	v_add_co_u32_e32 v16, vcc, s0, v6
	s_mov_b32 s0, 0xa208000
	s_nop 0
	v_addc_co_u32_e32 v17, vcc, 0, v7, vcc
	v_add_co_u32_e32 v18, vcc, s0, v6
	s_mov_b32 s0, 0xa209000
	s_nop 0
	v_addc_co_u32_e32 v19, vcc, 0, v7, vcc
	v_add_co_u32_e32 v20, vcc, s0, v6
	s_mov_b32 s0, 0xa20b000
	s_nop 0
	v_addc_co_u32_e32 v21, vcc, 0, v7, vcc
	v_add_co_u32_e32 v22, vcc, s0, v6
	s_mov_b32 s0, 0xa20c000
	s_nop 0
	v_addc_co_u32_e32 v23, vcc, 0, v7, vcc
	v_add_co_u32_e32 v24, vcc, s0, v6
	s_mov_b32 s0, 0xa20e000
	s_nop 0
	v_addc_co_u32_e32 v25, vcc, 0, v7, vcc
	v_add_co_u32_e32 v26, vcc, s0, v6
	s_mov_b32 s0, 0xa20f000
	s_nop 0
	v_addc_co_u32_e32 v27, vcc, 0, v7, vcc
	v_add_co_u32_e32 v28, vcc, s0, v6
	s_mov_b32 s0, 0xa211000
	s_nop 0
	v_addc_co_u32_e32 v29, vcc, 0, v7, vcc
	global_load_ushort v71, v[14:15], off
	global_load_ushort v88, v[16:17], off offset:2048
	global_load_ushort v89, v[18:19], off
	global_load_ushort v90, v[20:21], off offset:2048
	global_load_ushort v91, v[22:23], off
	global_load_ushort v92, v[24:25], off offset:2048
	global_load_ushort v93, v[26:27], off
	global_load_ushort v94, v[28:29], off offset:2048
	v_add_co_u32_e32 v14, vcc, s0, v6
	s_mov_b32 s0, 0xa212000
	s_nop 0
	v_addc_co_u32_e32 v15, vcc, 0, v7, vcc
	v_add_co_u32_e32 v16, vcc, s0, v6
	s_mov_b32 s0, 0xa214000
	s_nop 0
	v_addc_co_u32_e32 v17, vcc, 0, v7, vcc
	v_add_co_u32_e32 v18, vcc, s0, v6
	s_mov_b32 s0, 0xa215000
	s_nop 0
	v_addc_co_u32_e32 v19, vcc, 0, v7, vcc
	v_add_co_u32_e32 v20, vcc, s0, v6
	s_mov_b32 s0, 0xa217000
	s_nop 0
	v_addc_co_u32_e32 v21, vcc, 0, v7, vcc
	v_add_co_u32_e32 v22, vcc, s0, v6
	s_mov_b32 s0, 0xa218000
	s_nop 0
	v_addc_co_u32_e32 v23, vcc, 0, v7, vcc
	v_add_co_u32_e32 v24, vcc, s0, v6
	s_mov_b32 s0, 0xa21a000
	s_nop 0
	v_addc_co_u32_e32 v25, vcc, 0, v7, vcc
	v_add_co_u32_e32 v26, vcc, s0, v6
	s_mov_b32 s0, 0xa21b000
	s_nop 0
	v_addc_co_u32_e32 v27, vcc, 0, v7, vcc
	v_add_co_u32_e32 v28, vcc, s0, v6
	s_mov_b32 s0, 0xa21d000
	s_nop 0
	v_addc_co_u32_e32 v29, vcc, 0, v7, vcc
	global_load_ushort v98, v[14:15], off
	global_load_ushort v99, v[16:17], off offset:2048
	global_load_ushort v100, v[18:19], off
	global_load_ushort v102, v[20:21], off offset:2048
	global_load_ushort v105, v[22:23], off
	global_load_ushort v106, v[24:25], off offset:2048
	global_load_ushort v107, v[26:27], off
	global_load_ushort v108, v[28:29], off offset:2048
	v_add_co_u32_e32 v14, vcc, s0, v6
	s_mov_b32 s0, 0xa21e000
	s_nop 0
	v_addc_co_u32_e32 v15, vcc, 0, v7, vcc
	v_add_co_u32_e32 v16, vcc, s0, v6
	s_mov_b32 s0, 0xa220000
	s_nop 0
	v_addc_co_u32_e32 v17, vcc, 0, v7, vcc
	v_add_co_u32_e32 v18, vcc, s0, v6
	s_mov_b32 s0, 0xa221000
	s_nop 0
	v_addc_co_u32_e32 v19, vcc, 0, v7, vcc
	v_add_co_u32_e32 v20, vcc, s0, v6
	s_mov_b32 s0, 0xa223000
	s_nop 0
	v_addc_co_u32_e32 v21, vcc, 0, v7, vcc
	v_add_co_u32_e32 v22, vcc, s0, v6
	s_mov_b32 s0, 0xa224000
	s_nop 0
	v_addc_co_u32_e32 v23, vcc, 0, v7, vcc
	v_add_co_u32_e32 v24, vcc, s0, v6
	s_mov_b32 s0, 0xa226000
	s_nop 0
	v_addc_co_u32_e32 v25, vcc, 0, v7, vcc
	v_add_co_u32_e32 v26, vcc, s0, v6
	s_mov_b32 s0, 0xa227000
	s_nop 0
	v_addc_co_u32_e32 v27, vcc, 0, v7, vcc
	v_add_co_u32_e32 v28, vcc, s0, v6
	s_mov_b32 s0, 0xa229000
	s_nop 0
	v_addc_co_u32_e32 v29, vcc, 0, v7, vcc
	global_load_ushort v109, v[14:15], off
	global_load_ushort v110, v[16:17], off offset:2048
	global_load_ushort v111, v[18:19], off
	global_load_ushort v112, v[20:21], off offset:2048
	global_load_ushort v113, v[22:23], off
	global_load_ushort v114, v[24:25], off offset:2048
	global_load_ushort v115, v[26:27], off
	global_load_ushort v116, v[28:29], off offset:2048
	v_add_co_u32_e32 v14, vcc, s0, v6
	s_mov_b32 s0, 0xa22a000
	s_nop 0
	v_addc_co_u32_e32 v15, vcc, 0, v7, vcc
	v_add_co_u32_e32 v16, vcc, s0, v6
	s_mov_b32 s0, 0xa22c000
	s_nop 0
	v_addc_co_u32_e32 v17, vcc, 0, v7, vcc
	v_add_co_u32_e32 v18, vcc, s0, v6
	s_mov_b32 s0, 0xa22d000
	s_nop 0
	v_addc_co_u32_e32 v19, vcc, 0, v7, vcc
	v_add_co_u32_e32 v20, vcc, s0, v6
	s_mov_b32 s0, 0xa22f000
	s_nop 0
	v_addc_co_u32_e32 v21, vcc, 0, v7, vcc
	v_add_co_u32_e32 v6, vcc, s0, v6
	s_ashr_i32 s97, s96, 31
	s_nop 0
	v_addc_co_u32_e32 v7, vcc, 0, v7, vcc
	global_load_ushort v117, v[14:15], off
	global_load_ushort v118, v[16:17], off offset:2048
	global_load_ushort v119, v[18:19], off
	global_load_ushort v120, v[20:21], off offset:2048
	global_load_ushort v121, v[6:7], off
	global_load_ushort v101, v[8:9], off offset:2048
	global_load_ushort v103, v[10:11], off
	global_load_ushort v104, v[12:13], off offset:2048
	global_load_dwordx4 v[50:53], v[4:5], off
	s_ashr_i32 s35, s34, 31
	v_lshlrev_b32_e32 v70, 1, v2
	v_mbcnt_lo_u32_b32 v2, -1, 0
	s_lshl_b64 s[10:11], s[96:97], 8
	s_lshl_b64 s[42:43], s[34:35], 8
	s_movk_i32 s35, 0x1000
	s_movk_i32 s63, 0x4000
	s_movk_i32 s70, 0x5000
	s_mov_b32 s71, 0x9000
	s_mov_b32 s72, 0xc000
	s_mov_b32 s73, 0xd000
	s_mov_b32 s74, 0x10000
	s_mov_b32 s75, 0x15000
	s_movk_i32 s76, 0x3000
	s_movk_i32 s77, 0x90
	s_mov_b32 s78, 0xbfb8aa3b
	s_mov_b32 s79, 0x800000
	s_mov_b32 s80, 0x3f317217
	s_mov_b32 s81, 0x7f800000
	s_movk_i32 s82, 0x7fff
	s_movk_i32 s83, 0x88
	v_mbcnt_hi_u32_b32 v95, -1, v2
	v_mov_b32_e32 v96, 0x358637bd
	v_mov_b32_e32 v97, 0x41b17218
	s_mov_b32 s84, s96
	s_branch .LBB0_700

; #define SEAM(k) do { if (IN(k) && IN((k) + 1)) { if ((k) == 0 && a.ph_hi < 0) cg::this_grid().sync(); xcd_barrier(xbar); } } while (0)
; __device__ __forceinline__ void xcd_barrier(const XcdBarrier& b) {
;     asm volatile("s_waitcnt vmcnt(0)" ::: "memory");
;     __syncthreads();
;     if (threadIdx.x == 0) {
;         unsigned* bar = b.bar;
;         __builtin_amdgcn_s_waitcnt(0);
;         unsigned nloc = b.st[0], nx = b.st[1];
;         if (nloc == 0u) { xcd_barrier_complete(bar, b.x, nloc, nx); b.st[0] = nloc; b.st[1] = nx; }
; __global__ void __launch_bounds__(512, 2) fwd(Args a) {
;     ...
;     SEAM(4);
.LBB0_721:
	s_setprio 0
	s_cmp_gt_i32 s31, 5
	s_cselect_b64 s[0:1], -1, 0
	s_and_b64 s[4:5], s[4:5], s[0:1]
	s_andn2_b64 vcc, exec, s[4:5]
	s_cbranch_vccnz .LBB0_771
	s_waitcnt vmcnt(0)
	v_cmp_eq_u32_e32 vcc, 0, v0
	s_waitcnt lgkmcnt(0)
	s_barrier
	s_and_saveexec_b64 s[4:5], vcc
	s_cbranch_execz .LBB0_770
	v_mov_b32_e32 v2, s97
	s_waitcnt vmcnt(0) expcnt(0) lgkmcnt(0)
	ds_read_b32 v4, v2
	ds_read_b32 v2, v2 offset:4
	s_waitcnt lgkmcnt(1)
	v_cmp_ne_u32_e32 vcc, 0, v4
	s_cbranch_vccnz .LBB0_738
	v_readlane_b32 s6, v252, 8
	v_readlane_b32 s7, v252, 9
	s_load_dwordx2 s[10:11], s[6:7], 0x4
	s_add_u32 s6, s28, 0x1000
	s_addc_u32 s7, s29, 0
	s_add_u32 s8, s28, 0x1100
	s_addc_u32 s9, s29, 0
	s_waitcnt lgkmcnt(0)
	s_mul_i32 s3, s10, s34
	s_add_u32 s10, s28, 0x1200
	s_mul_i32 s3, s3, s11
	s_addc_u32 s11, s29, 0
	s_add_u32 s16, s28, 0x1300
	s_addc_u32 s17, s29, 0
	s_mov_b32 s35, 1
	v_mov_b32_e32 v18, 0
	s_branch .LBB0_726
